# FoX unit epilogue: the 16 gate loads are issued right after the last PV MFMA into dead registers
# speedup vs baseline: 1.0079x; 1.0079x over previous
.Lfx_tail_done:
	s_cmp_lg_u32 s42, 0
	s_cbranch_scc1 .Lfx_nogp
	v_lshlrev_b64 v[236:237], 11, v[160:161]
	v_lshl_add_u64 v[236:237], v[156:157], 0, v[236:237]
	global_load_dwordx2 v[196:197], v[236:237], off
	global_load_dwordx2 v[198:199], v[236:237], off offset:16
	global_load_dwordx2 v[200:201], v[236:237], off offset:32
	global_load_dwordx2 v[202:203], v[236:237], off offset:48
	global_load_dwordx2 v[204:205], v[236:237], off offset:64
	global_load_dwordx2 v[206:207], v[236:237], off offset:80
	global_load_dwordx2 v[208:209], v[236:237], off offset:96
	global_load_dwordx2 v[210:211], v[236:237], off offset:112
	global_load_dwordx2 v[212:213], v[236:237], off offset:128
	global_load_dwordx2 v[214:215], v[236:237], off offset:144
	global_load_dwordx2 v[216:217], v[236:237], off offset:160
	global_load_dwordx2 v[218:219], v[236:237], off offset:176
	global_load_dwordx2 v[220:221], v[236:237], off offset:192
	global_load_dwordx2 v[222:223], v[236:237], off offset:208
	global_load_dwordx2 v[224:225], v[236:237], off offset:224
	global_load_dwordx2 v[226:227], v[236:237], off offset:240

.LBB0_563:
	s_cmpk_gt_u32 s39, 0xff
	s_waitcnt lgkmcnt(0)
	s_barrier
	s_cbranch_scc1 .LBB0_543
	v_lshlrev_b64 v[2:3], 11, v[160:161]
	ds_read2st64_b32 v[8:9], v7 offset0:64 offset1:65
	v_lshl_add_u64 v[4:5], v[156:157], 0, v[2:3]
	v_max_f32_e32 v0, v192, v192
	s_waitcnt lgkmcnt(0)
	v_max_f32_e32 v6, v8, v8
	v_max_f32_e32 v0, v0, v6
	v_sub_f32_e32 v6, v192, v0
	v_sub_f32_e32 v0, v8, v0
	v_exp_f32_e32 v83, v0
	v_exp_f32_e32 v82, v6
	v_mov_b32_e32 v163, v9
	ds_read2st64_b32 v[84:85], v7 offset1:1
	ds_read2st64_b32 v[86:87], v7 offset0:2 offset1:3
	ds_read2st64_b32 v[88:89], v7 offset0:4 offset1:5
	ds_read2st64_b32 v[90:91], v7 offset0:6 offset1:7
	v_mul_f32_e32 v0, v9, v83
	v_pk_fma_f32 v[8:9], v[162:163], v[82:83], v[0:1] op_sel_hi:[1,1,0]
	v_lshlrev_b64 v[2:3], 12, v[160:161]
	v_mov_b32_e32 v0, v8
	s_nop 1
	v_permlane32_swap_b32_e32 v8, v0
	v_add_f32_e32 v0, v8, v0
	v_div_scale_f32 v6, s[4:5], v0, v0, 1.0
	v_rcp_f32_e32 v98, v6
	v_div_scale_f32 v99, vcc, 1.0, v0, 1.0
	ds_read2st64_b32 v[8:9], v7 offset0:8 offset1:9
	ds_read2st64_b32 v[92:93], v7 offset0:10 offset1:11
	ds_read2st64_b32 v[94:95], v7 offset0:12 offset1:13
	ds_read2st64_b32 v[96:97], v7 offset0:14 offset1:15
	v_fma_f32 v100, -v6, v98, 1.0
	v_fmac_f32_e32 v98, v100, v98
	v_mul_f32_e32 v100, v99, v98
	v_fma_f32 v101, -v6, v100, v99
	v_fmac_f32_e32 v100, v101, v98
	v_fma_f32 v6, -v6, v100, v99
	v_div_fmas_f32 v6, v6, v98, v100
	v_div_fixup_f32 v6, v6, v0, 1.0
	v_mul_f32_e32 v0, v82, v6
	v_mul_f32_e32 v6, v83, v6
	s_waitcnt lgkmcnt(7)
	v_pk_mul_f32 v[82:83], v[6:7], v[84:85] op_sel_hi:[0,1]
	s_waitcnt lgkmcnt(6)
	v_pk_mul_f32 v[84:85], v[6:7], v[86:87] op_sel_hi:[0,1]
	s_waitcnt lgkmcnt(5)
	v_pk_mul_f32 v[86:87], v[6:7], v[88:89] op_sel_hi:[0,1]
	s_waitcnt lgkmcnt(4)
	v_pk_mul_f32 v[88:89], v[6:7], v[90:91] op_sel_hi:[0,1]
	s_waitcnt lgkmcnt(3)
	v_pk_mul_f32 v[8:9], v[6:7], v[8:9] op_sel_hi:[0,1]
	s_waitcnt lgkmcnt(2)
	v_pk_mul_f32 v[90:91], v[6:7], v[92:93] op_sel_hi:[0,1]
	v_pk_fma_f32 v[64:65], v[64:65], v[0:1], v[82:83] op_sel_hi:[1,0,1]
	v_pk_fma_f32 v[66:67], v[66:67], v[0:1], v[84:85] op_sel_hi:[1,0,1]
	v_pk_fma_f32 v[70:71], v[70:71], v[0:1], v[88:89] op_sel_hi:[1,0,1]
	v_pk_fma_f32 v[8:9], v[72:73], v[0:1], v[8:9] op_sel_hi:[1,0,1]
	v_pk_fma_f32 v[72:73], v[74:75], v[0:1], v[90:91] op_sel_hi:[1,0,1]
	s_waitcnt lgkmcnt(1)
	v_pk_mul_f32 v[92:93], v[6:7], v[94:95] op_sel_hi:[0,1]
	v_pk_fma_f32 v[68:69], v[68:69], v[0:1], v[86:87] op_sel_hi:[1,0,1]
	v_lshl_add_u64 v[2:3], v[158:159], 0, v[2:3]
	s_waitcnt vmcnt(3)
	v_lshlrev_b32_e32 v74, 16, v196
	v_and_b32_e32 v75, 0xffff0000, v196
	v_lshlrev_b32_e32 v10, 16, v197
	v_and_b32_e32 v11, 0xffff0000, v197
	s_waitcnt vmcnt(2)
	v_lshlrev_b32_e32 v82, 16, v198
	v_and_b32_e32 v83, 0xffff0000, v198
	v_lshlrev_b32_e32 v12, 16, v199
	v_and_b32_e32 v13, 0xffff0000, v199
	s_waitcnt vmcnt(1)
	v_lshlrev_b32_e32 v84, 16, v200
	v_and_b32_e32 v85, 0xffff0000, v200
	v_lshlrev_b32_e32 v14, 16, v201
	v_and_b32_e32 v15, 0xffff0000, v201
	v_pk_mul_f32 v[64:65], v[64:65], v[74:75]
	v_pk_mul_f32 v[10:11], v[66:67], v[10:11]
	v_pk_mul_f32 v[12:13], v[70:71], v[12:13]
	v_pk_mul_f32 v[14:15], v[72:73], v[14:15]
	v_pk_mul_f32 v[66:67], v[68:69], v[82:83]
	v_pk_mul_f32 v[68:69], v[8:9], v[84:85]
	v_cvt_pk_bf16_f32 v8, v64, v65
	v_cvt_pk_bf16_f32 v9, v10, v11
	v_cvt_pk_bf16_f32 v11, v12, v13
	v_cvt_pk_bf16_f32 v13, v14, v15
	v_pk_fma_f32 v[14:15], v[76:77], v[0:1], v[92:93] op_sel_hi:[1,0,1]
	s_waitcnt vmcnt(0)
	v_lshlrev_b32_e32 v64, 16, v202
	v_and_b32_e32 v65, 0xffff0000, v202
	v_pk_mul_f32 v[14:15], v[14:15], v[64:65]
	s_waitcnt lgkmcnt(0)
	v_pk_mul_f32 v[64:65], v[6:7], v[96:97] op_sel_hi:[0,1]
	v_cvt_pk_bf16_f32 v10, v66, v67
	v_pk_fma_f32 v[64:65], v[78:79], v[0:1], v[64:65] op_sel_hi:[1,0,1]
	v_lshlrev_b32_e32 v66, 16, v203
	v_and_b32_e32 v67, 0xffff0000, v203
	v_pk_mul_f32 v[64:65], v[64:65], v[66:67]
	v_cvt_pk_bf16_f32 v12, v68, v69
	v_cvt_pk_bf16_f32 v14, v14, v15
	v_cvt_pk_bf16_f32 v15, v64, v65
	v_permlane32_swap_b32_e32 v8, v10
	v_permlane32_swap_b32_e32 v9, v11
	v_permlane32_swap_b32_e32 v12, v14
	v_permlane32_swap_b32_e32 v13, v15
	global_store_dwordx4 v[2:3], v[8:11], off
	global_store_dwordx4 v[2:3], v[12:15], off offset:32
	ds_read2st64_b32 v[64:65], v7 offset0:16 offset1:17
	ds_read2st64_b32 v[66:67], v7 offset0:18 offset1:19
	ds_read2st64_b32 v[68:69], v7 offset0:20 offset1:21
	ds_read2st64_b32 v[70:71], v7 offset0:22 offset1:23
	ds_read2st64_b32 v[72:73], v7 offset0:24 offset1:25
	ds_read2st64_b32 v[74:75], v7 offset0:26 offset1:27
	ds_read2st64_b32 v[76:77], v7 offset0:28 offset1:29
	ds_read2st64_b32 v[78:79], v7 offset0:30 offset1:31
	s_waitcnt lgkmcnt(7)
	v_pk_mul_f32 v[64:65], v[6:7], v[64:65] op_sel_hi:[0,1]
	s_waitcnt lgkmcnt(6)
	v_pk_mul_f32 v[66:67], v[6:7], v[66:67] op_sel_hi:[0,1]
	s_waitcnt lgkmcnt(5)
	v_pk_mul_f32 v[68:69], v[6:7], v[68:69] op_sel_hi:[0,1]
	s_waitcnt lgkmcnt(4)
	v_pk_mul_f32 v[70:71], v[6:7], v[70:71] op_sel_hi:[0,1]
	s_waitcnt lgkmcnt(3)
	v_pk_mul_f32 v[72:73], v[6:7], v[72:73] op_sel_hi:[0,1]
	s_waitcnt lgkmcnt(2)
	v_pk_mul_f32 v[74:75], v[6:7], v[74:75] op_sel_hi:[0,1]
	s_waitcnt lgkmcnt(1)
	v_pk_mul_f32 v[76:77], v[6:7], v[76:77] op_sel_hi:[0,1]
	s_waitcnt lgkmcnt(0)
	v_pk_mul_f32 v[78:79], v[6:7], v[78:79] op_sel_hi:[0,1]
	v_pk_fma_f32 v[48:49], v[48:49], v[0:1], v[64:65] op_sel_hi:[1,0,1]
	v_pk_fma_f32 v[50:51], v[50:51], v[0:1], v[66:67] op_sel_hi:[1,0,1]
	v_pk_fma_f32 v[52:53], v[52:53], v[0:1], v[68:69] op_sel_hi:[1,0,1]
	v_pk_fma_f32 v[54:55], v[54:55], v[0:1], v[70:71] op_sel_hi:[1,0,1]
	v_pk_fma_f32 v[56:57], v[56:57], v[0:1], v[72:73] op_sel_hi:[1,0,1]
	v_pk_fma_f32 v[58:59], v[58:59], v[0:1], v[74:75] op_sel_hi:[1,0,1]
	v_pk_fma_f32 v[60:61], v[60:61], v[0:1], v[76:77] op_sel_hi:[1,0,1]
	v_pk_fma_f32 v[62:63], v[62:63], v[0:1], v[78:79] op_sel_hi:[1,0,1]
	s_waitcnt vmcnt(3)
	v_lshlrev_b32_e32 v64, 16, v204
	v_and_b32_e32 v65, 0xffff0000, v204
	v_lshlrev_b32_e32 v8, 16, v205
	v_and_b32_e32 v9, 0xffff0000, v205
	s_waitcnt vmcnt(2)
	v_lshlrev_b32_e32 v66, 16, v206
	v_and_b32_e32 v67, 0xffff0000, v206
	v_lshlrev_b32_e32 v10, 16, v207
	v_and_b32_e32 v11, 0xffff0000, v207
	s_waitcnt vmcnt(1)
	v_lshlrev_b32_e32 v68, 16, v208
	v_and_b32_e32 v69, 0xffff0000, v208
	v_lshlrev_b32_e32 v12, 16, v209
	v_and_b32_e32 v13, 0xffff0000, v209
	s_waitcnt vmcnt(0)
	v_lshlrev_b32_e32 v70, 16, v210
	v_and_b32_e32 v71, 0xffff0000, v210
	v_lshlrev_b32_e32 v14, 16, v211
	v_and_b32_e32 v15, 0xffff0000, v211
	v_pk_mul_f32 v[48:49], v[48:49], v[64:65]
	v_pk_mul_f32 v[50:51], v[50:51], v[8:9]
	v_pk_mul_f32 v[52:53], v[52:53], v[66:67]
	v_pk_mul_f32 v[54:55], v[54:55], v[10:11]
	v_pk_mul_f32 v[56:57], v[56:57], v[68:69]
	v_pk_mul_f32 v[58:59], v[58:59], v[12:13]
	v_pk_mul_f32 v[60:61], v[60:61], v[70:71]
	v_pk_mul_f32 v[62:63], v[62:63], v[14:15]
	v_cvt_pk_bf16_f32 v8, v48, v49
	v_cvt_pk_bf16_f32 v9, v50, v51
	v_cvt_pk_bf16_f32 v10, v52, v53
	v_cvt_pk_bf16_f32 v11, v54, v55
	v_cvt_pk_bf16_f32 v12, v56, v57
	v_cvt_pk_bf16_f32 v13, v58, v59
	v_cvt_pk_bf16_f32 v14, v60, v61
	v_cvt_pk_bf16_f32 v15, v62, v63
	v_permlane32_swap_b32_e32 v8, v10
	v_permlane32_swap_b32_e32 v9, v11
	v_permlane32_swap_b32_e32 v12, v14
	v_permlane32_swap_b32_e32 v13, v15
	global_store_dwordx4 v[2:3], v[8:11], off offset:64
	global_store_dwordx4 v[2:3], v[12:15], off offset:96
	ds_read2st64_b32 v[48:49], v7 offset0:32 offset1:33
	ds_read2st64_b32 v[50:51], v7 offset0:34 offset1:35
	ds_read2st64_b32 v[52:53], v7 offset0:36 offset1:37
	ds_read2st64_b32 v[54:55], v7 offset0:38 offset1:39
	ds_read2st64_b32 v[56:57], v7 offset0:40 offset1:41
	ds_read2st64_b32 v[58:59], v7 offset0:42 offset1:43
	ds_read2st64_b32 v[60:61], v7 offset0:44 offset1:45
	ds_read2st64_b32 v[62:63], v7 offset0:46 offset1:47
	s_waitcnt lgkmcnt(7)
	v_pk_mul_f32 v[48:49], v[6:7], v[48:49] op_sel_hi:[0,1]
	s_waitcnt lgkmcnt(6)
	v_pk_mul_f32 v[50:51], v[6:7], v[50:51] op_sel_hi:[0,1]
	s_waitcnt lgkmcnt(5)
	v_pk_mul_f32 v[52:53], v[6:7], v[52:53] op_sel_hi:[0,1]
	s_waitcnt lgkmcnt(4)
	v_pk_mul_f32 v[54:55], v[6:7], v[54:55] op_sel_hi:[0,1]
	s_waitcnt lgkmcnt(3)
	v_pk_mul_f32 v[56:57], v[6:7], v[56:57] op_sel_hi:[0,1]
	s_waitcnt lgkmcnt(2)
	v_pk_mul_f32 v[58:59], v[6:7], v[58:59] op_sel_hi:[0,1]
	s_waitcnt lgkmcnt(1)
	v_pk_mul_f32 v[60:61], v[6:7], v[60:61] op_sel_hi:[0,1]
	s_waitcnt lgkmcnt(0)
	v_pk_mul_f32 v[62:63], v[6:7], v[62:63] op_sel_hi:[0,1]
	v_pk_fma_f32 v[32:33], v[32:33], v[0:1], v[48:49] op_sel_hi:[1,0,1]
	v_pk_fma_f32 v[34:35], v[34:35], v[0:1], v[50:51] op_sel_hi:[1,0,1]
	v_pk_fma_f32 v[36:37], v[36:37], v[0:1], v[52:53] op_sel_hi:[1,0,1]
	v_pk_fma_f32 v[38:39], v[38:39], v[0:1], v[54:55] op_sel_hi:[1,0,1]
	v_pk_fma_f32 v[40:41], v[40:41], v[0:1], v[56:57] op_sel_hi:[1,0,1]
	v_pk_fma_f32 v[42:43], v[42:43], v[0:1], v[58:59] op_sel_hi:[1,0,1]
	v_pk_fma_f32 v[44:45], v[44:45], v[0:1], v[60:61] op_sel_hi:[1,0,1]
	v_pk_fma_f32 v[46:47], v[46:47], v[0:1], v[62:63] op_sel_hi:[1,0,1]
	s_waitcnt vmcnt(3)
	v_lshlrev_b32_e32 v48, 16, v212
	v_and_b32_e32 v49, 0xffff0000, v212
	v_lshlrev_b32_e32 v8, 16, v213
	v_and_b32_e32 v9, 0xffff0000, v213
	s_waitcnt vmcnt(2)
	v_lshlrev_b32_e32 v50, 16, v214
	v_and_b32_e32 v51, 0xffff0000, v214
	v_lshlrev_b32_e32 v10, 16, v215
	v_and_b32_e32 v11, 0xffff0000, v215
	s_waitcnt vmcnt(1)
	v_lshlrev_b32_e32 v52, 16, v216
	v_and_b32_e32 v53, 0xffff0000, v216
	v_lshlrev_b32_e32 v12, 16, v217
	v_and_b32_e32 v13, 0xffff0000, v217
	s_waitcnt vmcnt(0)
	v_lshlrev_b32_e32 v54, 16, v218
	v_and_b32_e32 v55, 0xffff0000, v218
	v_lshlrev_b32_e32 v14, 16, v219
	v_and_b32_e32 v15, 0xffff0000, v219
	v_pk_mul_f32 v[32:33], v[32:33], v[48:49]
	v_pk_mul_f32 v[34:35], v[34:35], v[8:9]
	v_pk_mul_f32 v[36:37], v[36:37], v[50:51]
	v_pk_mul_f32 v[38:39], v[38:39], v[10:11]
	v_pk_mul_f32 v[40:41], v[40:41], v[52:53]
	v_pk_mul_f32 v[42:43], v[42:43], v[12:13]
	v_pk_mul_f32 v[44:45], v[44:45], v[54:55]
	v_pk_mul_f32 v[46:47], v[46:47], v[14:15]
	v_cvt_pk_bf16_f32 v8, v32, v33
	v_cvt_pk_bf16_f32 v9, v34, v35
	v_cvt_pk_bf16_f32 v10, v36, v37
	v_cvt_pk_bf16_f32 v11, v38, v39
	v_cvt_pk_bf16_f32 v12, v40, v41
	v_cvt_pk_bf16_f32 v13, v42, v43
	v_cvt_pk_bf16_f32 v14, v44, v45
	v_cvt_pk_bf16_f32 v15, v46, v47
	v_permlane32_swap_b32_e32 v8, v10
	v_permlane32_swap_b32_e32 v9, v11
	v_permlane32_swap_b32_e32 v12, v14
	v_permlane32_swap_b32_e32 v13, v15
	global_store_dwordx4 v[2:3], v[8:11], off offset:128
	global_store_dwordx4 v[2:3], v[12:15], off offset:160
	ds_read2st64_b32 v[4:5], v7 offset0:48 offset1:49
	ds_read2st64_b32 v[32:33], v7 offset0:50 offset1:51
	ds_read2st64_b32 v[34:35], v7 offset0:52 offset1:53
	ds_read2st64_b32 v[36:37], v7 offset0:54 offset1:55
	ds_read2st64_b32 v[38:39], v7 offset0:56 offset1:57
	ds_read2st64_b32 v[40:41], v7 offset0:58 offset1:59
	ds_read2st64_b32 v[42:43], v7 offset0:60 offset1:61
	ds_read2st64_b32 v[44:45], v7 offset0:62 offset1:63
	s_waitcnt lgkmcnt(7)
	v_pk_mul_f32 v[4:5], v[6:7], v[4:5] op_sel_hi:[0,1]
	s_waitcnt lgkmcnt(6)
	v_pk_mul_f32 v[32:33], v[6:7], v[32:33] op_sel_hi:[0,1]
	s_waitcnt lgkmcnt(5)
	v_pk_mul_f32 v[34:35], v[6:7], v[34:35] op_sel_hi:[0,1]
	s_waitcnt lgkmcnt(4)
	v_pk_mul_f32 v[36:37], v[6:7], v[36:37] op_sel_hi:[0,1]
	s_waitcnt lgkmcnt(3)
	v_pk_mul_f32 v[38:39], v[6:7], v[38:39] op_sel_hi:[0,1]
	s_waitcnt lgkmcnt(2)
	v_pk_mul_f32 v[40:41], v[6:7], v[40:41] op_sel_hi:[0,1]
	s_waitcnt lgkmcnt(1)
	v_pk_mul_f32 v[42:43], v[6:7], v[42:43] op_sel_hi:[0,1]
	s_waitcnt lgkmcnt(0)
	v_pk_mul_f32 v[6:7], v[6:7], v[44:45] op_sel_hi:[0,1]
	v_pk_fma_f32 v[4:5], v[16:17], v[0:1], v[4:5] op_sel_hi:[1,0,1]
	v_pk_fma_f32 v[16:17], v[18:19], v[0:1], v[32:33] op_sel_hi:[1,0,1]
	v_pk_fma_f32 v[18:19], v[20:21], v[0:1], v[34:35] op_sel_hi:[1,0,1]
	v_pk_fma_f32 v[20:21], v[22:23], v[0:1], v[36:37] op_sel_hi:[1,0,1]
	v_pk_fma_f32 v[22:23], v[24:25], v[0:1], v[38:39] op_sel_hi:[1,0,1]
	v_pk_fma_f32 v[24:25], v[26:27], v[0:1], v[40:41] op_sel_hi:[1,0,1]
	v_pk_fma_f32 v[26:27], v[28:29], v[0:1], v[42:43] op_sel_hi:[1,0,1]
	v_pk_fma_f32 v[6:7], v[30:31], v[0:1], v[6:7] op_sel_hi:[1,0,1]
	s_waitcnt vmcnt(3)
	v_lshlrev_b32_e32 v28, 16, v220
	v_and_b32_e32 v29, 0xffff0000, v220
	v_lshlrev_b32_e32 v8, 16, v221
	v_and_b32_e32 v9, 0xffff0000, v221
	s_waitcnt vmcnt(2)
	v_lshlrev_b32_e32 v30, 16, v222
	v_and_b32_e32 v31, 0xffff0000, v222
	v_lshlrev_b32_e32 v10, 16, v223
	v_and_b32_e32 v11, 0xffff0000, v223
	s_waitcnt vmcnt(1)
	v_lshlrev_b32_e32 v32, 16, v224
	v_and_b32_e32 v33, 0xffff0000, v224
	v_lshlrev_b32_e32 v12, 16, v225
	v_and_b32_e32 v13, 0xffff0000, v225
	s_waitcnt vmcnt(0)
	v_lshlrev_b32_e32 v34, 16, v226
	v_and_b32_e32 v35, 0xffff0000, v226
	v_lshlrev_b32_e32 v14, 16, v227
	v_and_b32_e32 v15, 0xffff0000, v227
	v_pk_mul_f32 v[4:5], v[4:5], v[28:29]
	v_pk_mul_f32 v[8:9], v[16:17], v[8:9]
	v_pk_mul_f32 v[16:17], v[18:19], v[30:31]
	v_pk_mul_f32 v[10:11], v[20:21], v[10:11]
	v_pk_mul_f32 v[18:19], v[22:23], v[32:33]
	v_pk_mul_f32 v[12:13], v[24:25], v[12:13]
	v_pk_mul_f32 v[20:21], v[26:27], v[34:35]
	v_pk_mul_f32 v[14:15], v[6:7], v[14:15]
	v_cvt_pk_bf16_f32 v4, v4, v5
	v_cvt_pk_bf16_f32 v5, v8, v9
	v_cvt_pk_bf16_f32 v6, v16, v17
	v_cvt_pk_bf16_f32 v7, v10, v11
	v_cvt_pk_bf16_f32 v8, v18, v19
	v_cvt_pk_bf16_f32 v9, v12, v13
	v_cvt_pk_bf16_f32 v10, v20, v21
	v_cvt_pk_bf16_f32 v11, v14, v15
	v_permlane32_swap_b32_e32 v4, v6
	v_permlane32_swap_b32_e32 v5, v7
	v_permlane32_swap_b32_e32 v8, v10
	v_permlane32_swap_b32_e32 v9, v11
	global_store_dwordx4 v[2:3], v[4:7], off offset:192
	global_store_dwordx4 v[2:3], v[8:11], off offset:224
	s_branch .LBB0_543
